# top-k threshold search: row-max bracket + interval bisection, counting split between scalar popcount and per-lane addc
# speedup vs baseline: 1.0010x; 1.0010x over previous
.Ltk0_cn31:
.Ltk0_cvd:
.Ltk0_binit:
	v_mov_b32_e32 v160, 0
	v_mov_b32_e32 v161, 0
	v_max_u32_e32 v160, v160, v32
	v_max_u32_e32 v161, v161, v33
	v_max_u32_e32 v160, v160, v34
	v_max_u32_e32 v161, v161, v35
	v_max_u32_e32 v160, v160, v36
	v_max_u32_e32 v161, v161, v37
	v_max_u32_e32 v160, v160, v38
	v_max_u32_e32 v161, v161, v39
	s_cmp_le_u32 s23, 2
	s_cbranch_scc1 .Ltk0_mxd
	v_max_u32_e32 v160, v160, v40
	v_max_u32_e32 v161, v161, v41
	v_max_u32_e32 v160, v160, v42
	v_max_u32_e32 v161, v161, v43
	v_max_u32_e32 v160, v160, v44
	v_max_u32_e32 v161, v161, v45
	v_max_u32_e32 v160, v160, v46
	v_max_u32_e32 v161, v161, v47
	s_cmp_le_u32 s23, 4
	s_cbranch_scc1 .Ltk0_mxd
	v_max_u32_e32 v160, v160, v48
	v_max_u32_e32 v161, v161, v49
	v_max_u32_e32 v160, v160, v50
	v_max_u32_e32 v161, v161, v51
	v_max_u32_e32 v160, v160, v52
	v_max_u32_e32 v161, v161, v53
	v_max_u32_e32 v160, v160, v54
	v_max_u32_e32 v161, v161, v55
	s_cmp_le_u32 s23, 6
	s_cbranch_scc1 .Ltk0_mxd
	v_max_u32_e32 v160, v160, v56
	v_max_u32_e32 v161, v161, v57
	v_max_u32_e32 v160, v160, v58
	v_max_u32_e32 v161, v161, v59
	v_max_u32_e32 v160, v160, v60
	v_max_u32_e32 v161, v161, v61
	v_max_u32_e32 v160, v160, v62
	v_max_u32_e32 v161, v161, v63
	s_cmp_le_u32 s23, 8
	s_cbranch_scc1 .Ltk0_mxd
	v_max_u32_e32 v160, v160, v64
	v_max_u32_e32 v161, v161, v65
	v_max_u32_e32 v160, v160, v66
	v_max_u32_e32 v161, v161, v67
	v_max_u32_e32 v160, v160, v68
	v_max_u32_e32 v161, v161, v69
	v_max_u32_e32 v160, v160, v70
	v_max_u32_e32 v161, v161, v71
	s_cmp_le_u32 s23, 10
	s_cbranch_scc1 .Ltk0_mxd
	v_max_u32_e32 v160, v160, v72
	v_max_u32_e32 v161, v161, v73
	v_max_u32_e32 v160, v160, v74
	v_max_u32_e32 v161, v161, v75
	v_max_u32_e32 v160, v160, v76
	v_max_u32_e32 v161, v161, v77
	v_max_u32_e32 v160, v160, v78
	v_max_u32_e32 v161, v161, v79
	s_cmp_le_u32 s23, 12
	s_cbranch_scc1 .Ltk0_mxd
	v_max_u32_e32 v160, v160, v80
	v_max_u32_e32 v161, v161, v81
	v_max_u32_e32 v160, v160, v82
	v_max_u32_e32 v161, v161, v83
	v_max_u32_e32 v160, v160, v84
	v_max_u32_e32 v161, v161, v85
	v_max_u32_e32 v160, v160, v86
	v_max_u32_e32 v161, v161, v87
	s_cmp_le_u32 s23, 14
	s_cbranch_scc1 .Ltk0_mxd
	v_max_u32_e32 v160, v160, v88
	v_max_u32_e32 v161, v161, v89
	v_max_u32_e32 v160, v160, v90
	v_max_u32_e32 v161, v161, v91
	v_max_u32_e32 v160, v160, v92
	v_max_u32_e32 v161, v161, v93
	v_max_u32_e32 v160, v160, v94
	v_max_u32_e32 v161, v161, v95
	s_cmp_le_u32 s23, 16
	s_cbranch_scc1 .Ltk0_mxd
	v_max_u32_e32 v160, v160, v96
	v_max_u32_e32 v161, v161, v97
	v_max_u32_e32 v160, v160, v98
	v_max_u32_e32 v161, v161, v99
	v_max_u32_e32 v160, v160, v100
	v_max_u32_e32 v161, v161, v101
	v_max_u32_e32 v160, v160, v102
	v_max_u32_e32 v161, v161, v103
	s_cmp_le_u32 s23, 18
	s_cbranch_scc1 .Ltk0_mxd
	v_max_u32_e32 v160, v160, v104
	v_max_u32_e32 v161, v161, v105
	v_max_u32_e32 v160, v160, v106
	v_max_u32_e32 v161, v161, v107
	v_max_u32_e32 v160, v160, v108
	v_max_u32_e32 v161, v161, v109
	v_max_u32_e32 v160, v160, v110
	v_max_u32_e32 v161, v161, v111
	s_cmp_le_u32 s23, 20
	s_cbranch_scc1 .Ltk0_mxd
	v_max_u32_e32 v160, v160, v112
	v_max_u32_e32 v161, v161, v113
	v_max_u32_e32 v160, v160, v114
	v_max_u32_e32 v161, v161, v115
	v_max_u32_e32 v160, v160, v116
	v_max_u32_e32 v161, v161, v117
	v_max_u32_e32 v160, v160, v118
	v_max_u32_e32 v161, v161, v119
	s_cmp_le_u32 s23, 22
	s_cbranch_scc1 .Ltk0_mxd
	v_max_u32_e32 v160, v160, v120
	v_max_u32_e32 v161, v161, v121
	v_max_u32_e32 v160, v160, v122
	v_max_u32_e32 v161, v161, v123
	v_max_u32_e32 v160, v160, v124
	v_max_u32_e32 v161, v161, v125
	v_max_u32_e32 v160, v160, v126
	v_max_u32_e32 v161, v161, v127
	s_cmp_le_u32 s23, 24
	s_cbranch_scc1 .Ltk0_mxd
	v_max_u32_e32 v160, v160, v128
	v_max_u32_e32 v161, v161, v129
	v_max_u32_e32 v160, v160, v130
	v_max_u32_e32 v161, v161, v131
	v_max_u32_e32 v160, v160, v132
	v_max_u32_e32 v161, v161, v133
	v_max_u32_e32 v160, v160, v134
	v_max_u32_e32 v161, v161, v135
	s_cmp_le_u32 s23, 26
	s_cbranch_scc1 .Ltk0_mxd
	v_max_u32_e32 v160, v160, v136
	v_max_u32_e32 v161, v161, v137
	v_max_u32_e32 v160, v160, v138
	v_max_u32_e32 v161, v161, v139
	v_max_u32_e32 v160, v160, v140
	v_max_u32_e32 v161, v161, v141
	v_max_u32_e32 v160, v160, v142
	v_max_u32_e32 v161, v161, v143
	s_cmp_le_u32 s23, 28
	s_cbranch_scc1 .Ltk0_mxd
	v_max_u32_e32 v160, v160, v144
	v_max_u32_e32 v161, v161, v145
	v_max_u32_e32 v160, v160, v146
	v_max_u32_e32 v161, v161, v147
	v_max_u32_e32 v160, v160, v148
	v_max_u32_e32 v161, v161, v149
	v_max_u32_e32 v160, v160, v150
	v_max_u32_e32 v161, v161, v151
	s_cmp_le_u32 s23, 30
	s_cbranch_scc1 .Ltk0_mxd
	v_max_u32_e32 v160, v160, v152
	v_max_u32_e32 v161, v161, v153
	v_max_u32_e32 v160, v160, v154
	v_max_u32_e32 v161, v161, v155
	v_max_u32_e32 v160, v160, v156
	v_max_u32_e32 v161, v161, v157
	v_max_u32_e32 v160, v160, v158
	v_max_u32_e32 v161, v161, v159
.Ltk0_mxd:
	v_max_u32_e32 v160, v160, v161
	s_nop 1
	v_max_u32_dpp v160, v160, v160 quad_perm:[1,0,3,2] row_mask:0xf bank_mask:0xf
	s_nop 1
	v_max_u32_dpp v160, v160, v160 quad_perm:[2,3,0,1] row_mask:0xf bank_mask:0xf
	s_nop 1
	v_max_u32_dpp v160, v160, v160 row_half_mirror row_mask:0xf bank_mask:0xf
	s_nop 1
	v_max_u32_dpp v160, v160, v160 row_mirror row_mask:0xf bank_mask:0xf
	s_nop 1
	v_readlane_b32 s31, v160, 0
	v_readlane_b32 s82, v160, 16
	v_readlane_b32 s83, v160, 32
	v_readlane_b32 s93, v160, 48
	s_nop 3
	s_max_u32 s31, s31, s82
	s_max_u32 s83, s83, s93
	s_max_u32 s31, s31, s83
	s_add_u32 s21, s31, 1
	s_mov_b32 s20, 0
	s_and_b32 s30, s31, 0xff800000
	s_sub_u32 s30, s30, 0x1800000
	s_branch .Ltk0_count
.Ltk0_bloop:
	s_sub_u32 s31, s21, s20
	s_cmp_le_u32 s31, 1
	s_cbranch_scc1 .Ltk0_exh
	s_lshr_b32 s31, s31, 1
	s_add_u32 s30, s20, s31
.Ltk0_count:
	v_mov_b32_e32 v160, 0
	v_mov_b32_e32 v161, 0
	s_mov_b32 s22, 0
	v_cmp_le_u32_e64 s[34:35], s30, v32
	v_cmp_le_u32_e64 s[36:37], s30, v33
	v_cmp_le_u32_e64 s[48:49], s30, v34
	s_bcnt1_i32_b64 s82, s[34:35]
	v_cmp_le_u32_e64 s[50:51], s30, v35
	s_add_i32 s22, s22, s82
	v_addc_co_u32_e64 v160, vcc, 0, v160, s[48:49]
	s_bcnt1_i32_b64 s83, s[36:37]
	v_cmp_le_u32_e64 s[34:35], s30, v36
	s_add_i32 s22, s22, s83
	v_cmp_le_u32_e64 s[36:37], s30, v37
	s_bcnt1_i32_b64 s82, s[50:51]
	v_cmp_le_u32_e64 s[48:49], s30, v38
	s_add_i32 s22, s22, s82
	v_cmp_le_u32_e64 s[50:51], s30, v39
	s_bcnt1_i32_b64 s83, s[34:35]
	v_addc_co_u32_e64 v161, vcc, 0, v161, s[36:37]
	s_add_i32 s22, s22, s83
	v_addc_co_u32_e64 v160, vcc, 0, v160, s[50:51]
	s_bcnt1_i32_b64 s82, s[48:49]
	s_add_i32 s22, s22, s82
	s_cmp_le_u32 s23, 2
	s_cbranch_scc1 .Ltk0_bred
	v_cmp_le_u32_e64 s[34:35], s30, v40
	v_cmp_le_u32_e64 s[36:37], s30, v41
	v_cmp_le_u32_e64 s[48:49], s30, v42
	s_bcnt1_i32_b64 s82, s[34:35]
	v_cmp_le_u32_e64 s[50:51], s30, v43
	s_add_i32 s22, s22, s82
	v_addc_co_u32_e64 v160, vcc, 0, v160, s[48:49]
	s_bcnt1_i32_b64 s83, s[36:37]
	v_cmp_le_u32_e64 s[34:35], s30, v44
	s_add_i32 s22, s22, s83
	v_cmp_le_u32_e64 s[36:37], s30, v45
	s_bcnt1_i32_b64 s82, s[50:51]
	v_cmp_le_u32_e64 s[48:49], s30, v46
	s_add_i32 s22, s22, s82
	v_cmp_le_u32_e64 s[50:51], s30, v47
	s_bcnt1_i32_b64 s83, s[34:35]
	v_addc_co_u32_e64 v161, vcc, 0, v161, s[36:37]
	s_add_i32 s22, s22, s83
	v_addc_co_u32_e64 v160, vcc, 0, v160, s[50:51]
	s_bcnt1_i32_b64 s82, s[48:49]
	s_add_i32 s22, s22, s82
	s_cmp_le_u32 s23, 4
	s_cbranch_scc1 .Ltk0_bred
	v_cmp_le_u32_e64 s[34:35], s30, v48
	v_cmp_le_u32_e64 s[36:37], s30, v49
	v_cmp_le_u32_e64 s[48:49], s30, v50
	s_bcnt1_i32_b64 s82, s[34:35]
	v_cmp_le_u32_e64 s[50:51], s30, v51
	s_add_i32 s22, s22, s82
	v_addc_co_u32_e64 v160, vcc, 0, v160, s[48:49]
	s_bcnt1_i32_b64 s83, s[36:37]
	v_cmp_le_u32_e64 s[34:35], s30, v52
	s_add_i32 s22, s22, s83
	v_cmp_le_u32_e64 s[36:37], s30, v53
	s_bcnt1_i32_b64 s82, s[50:51]
	v_cmp_le_u32_e64 s[48:49], s30, v54
	s_add_i32 s22, s22, s82
	v_cmp_le_u32_e64 s[50:51], s30, v55
	s_bcnt1_i32_b64 s83, s[34:35]
	v_addc_co_u32_e64 v161, vcc, 0, v161, s[36:37]
	s_add_i32 s22, s22, s83
	v_addc_co_u32_e64 v160, vcc, 0, v160, s[50:51]
	s_bcnt1_i32_b64 s82, s[48:49]
	s_add_i32 s22, s22, s82
	s_cmp_le_u32 s23, 6
	s_cbranch_scc1 .Ltk0_bred
	v_cmp_le_u32_e64 s[34:35], s30, v56
	v_cmp_le_u32_e64 s[36:37], s30, v57
	v_cmp_le_u32_e64 s[48:49], s30, v58
	s_bcnt1_i32_b64 s82, s[34:35]
	v_cmp_le_u32_e64 s[50:51], s30, v59
	s_add_i32 s22, s22, s82
	v_addc_co_u32_e64 v160, vcc, 0, v160, s[48:49]
	s_bcnt1_i32_b64 s83, s[36:37]
	v_cmp_le_u32_e64 s[34:35], s30, v60
	s_add_i32 s22, s22, s83
	v_cmp_le_u32_e64 s[36:37], s30, v61
	s_bcnt1_i32_b64 s82, s[50:51]
	v_cmp_le_u32_e64 s[48:49], s30, v62
	s_add_i32 s22, s22, s82
	v_cmp_le_u32_e64 s[50:51], s30, v63
	s_bcnt1_i32_b64 s83, s[34:35]
	v_addc_co_u32_e64 v161, vcc, 0, v161, s[36:37]
	s_add_i32 s22, s22, s83
	v_addc_co_u32_e64 v160, vcc, 0, v160, s[50:51]
	s_bcnt1_i32_b64 s82, s[48:49]
	s_add_i32 s22, s22, s82
	s_cmp_le_u32 s23, 8
	s_cbranch_scc1 .Ltk0_bred
	v_cmp_le_u32_e64 s[34:35], s30, v64
	v_cmp_le_u32_e64 s[36:37], s30, v65
	v_cmp_le_u32_e64 s[48:49], s30, v66
	s_bcnt1_i32_b64 s82, s[34:35]
	v_cmp_le_u32_e64 s[50:51], s30, v67
	s_add_i32 s22, s22, s82
	v_addc_co_u32_e64 v160, vcc, 0, v160, s[48:49]
	s_bcnt1_i32_b64 s83, s[36:37]
	v_cmp_le_u32_e64 s[34:35], s30, v68
	s_add_i32 s22, s22, s83
	v_cmp_le_u32_e64 s[36:37], s30, v69
	s_bcnt1_i32_b64 s82, s[50:51]
	v_cmp_le_u32_e64 s[48:49], s30, v70
	s_add_i32 s22, s22, s82
	v_cmp_le_u32_e64 s[50:51], s30, v71
	s_bcnt1_i32_b64 s83, s[34:35]
	v_addc_co_u32_e64 v161, vcc, 0, v161, s[36:37]
	s_add_i32 s22, s22, s83
	v_addc_co_u32_e64 v160, vcc, 0, v160, s[50:51]
	s_bcnt1_i32_b64 s82, s[48:49]
	s_add_i32 s22, s22, s82
	s_cmp_le_u32 s23, 10
	s_cbranch_scc1 .Ltk0_bred
	v_cmp_le_u32_e64 s[34:35], s30, v72
	v_cmp_le_u32_e64 s[36:37], s30, v73
	v_cmp_le_u32_e64 s[48:49], s30, v74
	s_bcnt1_i32_b64 s82, s[34:35]
	v_cmp_le_u32_e64 s[50:51], s30, v75
	s_add_i32 s22, s22, s82
	v_addc_co_u32_e64 v160, vcc, 0, v160, s[48:49]
	s_bcnt1_i32_b64 s83, s[36:37]
	v_cmp_le_u32_e64 s[34:35], s30, v76
	s_add_i32 s22, s22, s83
	v_cmp_le_u32_e64 s[36:37], s30, v77
	s_bcnt1_i32_b64 s82, s[50:51]
	v_cmp_le_u32_e64 s[48:49], s30, v78
	s_add_i32 s22, s22, s82
	v_cmp_le_u32_e64 s[50:51], s30, v79
	s_bcnt1_i32_b64 s83, s[34:35]
	v_addc_co_u32_e64 v161, vcc, 0, v161, s[36:37]
	s_add_i32 s22, s22, s83
	v_addc_co_u32_e64 v160, vcc, 0, v160, s[50:51]
	s_bcnt1_i32_b64 s82, s[48:49]
	s_add_i32 s22, s22, s82
	s_cmp_le_u32 s23, 12
	s_cbranch_scc1 .Ltk0_bred
	v_cmp_le_u32_e64 s[34:35], s30, v80
	v_cmp_le_u32_e64 s[36:37], s30, v81
	v_cmp_le_u32_e64 s[48:49], s30, v82
	s_bcnt1_i32_b64 s82, s[34:35]
	v_cmp_le_u32_e64 s[50:51], s30, v83
	s_add_i32 s22, s22, s82
	v_addc_co_u32_e64 v160, vcc, 0, v160, s[48:49]
	s_bcnt1_i32_b64 s83, s[36:37]
	v_cmp_le_u32_e64 s[34:35], s30, v84
	s_add_i32 s22, s22, s83
	v_cmp_le_u32_e64 s[36:37], s30, v85
	s_bcnt1_i32_b64 s82, s[50:51]
	v_cmp_le_u32_e64 s[48:49], s30, v86
	s_add_i32 s22, s22, s82
	v_cmp_le_u32_e64 s[50:51], s30, v87
	s_bcnt1_i32_b64 s83, s[34:35]
	v_addc_co_u32_e64 v161, vcc, 0, v161, s[36:37]
	s_add_i32 s22, s22, s83
	v_addc_co_u32_e64 v160, vcc, 0, v160, s[50:51]
	s_bcnt1_i32_b64 s82, s[48:49]
	s_add_i32 s22, s22, s82
	s_cmp_le_u32 s23, 14
	s_cbranch_scc1 .Ltk0_bred
	v_cmp_le_u32_e64 s[34:35], s30, v88
	v_cmp_le_u32_e64 s[36:37], s30, v89
	v_cmp_le_u32_e64 s[48:49], s30, v90
	s_bcnt1_i32_b64 s82, s[34:35]
	v_cmp_le_u32_e64 s[50:51], s30, v91
	s_add_i32 s22, s22, s82
	v_addc_co_u32_e64 v160, vcc, 0, v160, s[48:49]
	s_bcnt1_i32_b64 s83, s[36:37]
	v_cmp_le_u32_e64 s[34:35], s30, v92
	s_add_i32 s22, s22, s83
	v_cmp_le_u32_e64 s[36:37], s30, v93
	s_bcnt1_i32_b64 s82, s[50:51]
	v_cmp_le_u32_e64 s[48:49], s30, v94
	s_add_i32 s22, s22, s82
	v_cmp_le_u32_e64 s[50:51], s30, v95
	s_bcnt1_i32_b64 s83, s[34:35]
	v_addc_co_u32_e64 v161, vcc, 0, v161, s[36:37]
	s_add_i32 s22, s22, s83
	v_addc_co_u32_e64 v160, vcc, 0, v160, s[50:51]
	s_bcnt1_i32_b64 s82, s[48:49]
	s_add_i32 s22, s22, s82
	s_cmp_le_u32 s23, 16
	s_cbranch_scc1 .Ltk0_bred
	v_cmp_le_u32_e64 s[34:35], s30, v96
	v_cmp_le_u32_e64 s[36:37], s30, v97
	v_cmp_le_u32_e64 s[48:49], s30, v98
	s_bcnt1_i32_b64 s82, s[34:35]
	v_cmp_le_u32_e64 s[50:51], s30, v99
	s_add_i32 s22, s22, s82
	v_addc_co_u32_e64 v160, vcc, 0, v160, s[48:49]
	s_bcnt1_i32_b64 s83, s[36:37]
	v_cmp_le_u32_e64 s[34:35], s30, v100
	s_add_i32 s22, s22, s83
	v_cmp_le_u32_e64 s[36:37], s30, v101
	s_bcnt1_i32_b64 s82, s[50:51]
	v_cmp_le_u32_e64 s[48:49], s30, v102
	s_add_i32 s22, s22, s82
	v_cmp_le_u32_e64 s[50:51], s30, v103
	s_bcnt1_i32_b64 s83, s[34:35]
	v_addc_co_u32_e64 v161, vcc, 0, v161, s[36:37]
	s_add_i32 s22, s22, s83
	v_addc_co_u32_e64 v160, vcc, 0, v160, s[50:51]
	s_bcnt1_i32_b64 s82, s[48:49]
	s_add_i32 s22, s22, s82
	s_cmp_le_u32 s23, 18
	s_cbranch_scc1 .Ltk0_bred
	v_cmp_le_u32_e64 s[34:35], s30, v104
	v_cmp_le_u32_e64 s[36:37], s30, v105
	v_cmp_le_u32_e64 s[48:49], s30, v106
	s_bcnt1_i32_b64 s82, s[34:35]
	v_cmp_le_u32_e64 s[50:51], s30, v107
	s_add_i32 s22, s22, s82
	v_addc_co_u32_e64 v160, vcc, 0, v160, s[48:49]
	s_bcnt1_i32_b64 s83, s[36:37]
	v_cmp_le_u32_e64 s[34:35], s30, v108
	s_add_i32 s22, s22, s83
	v_cmp_le_u32_e64 s[36:37], s30, v109
	s_bcnt1_i32_b64 s82, s[50:51]
	v_cmp_le_u32_e64 s[48:49], s30, v110
	s_add_i32 s22, s22, s82
	v_cmp_le_u32_e64 s[50:51], s30, v111
	s_bcnt1_i32_b64 s83, s[34:35]
	v_addc_co_u32_e64 v161, vcc, 0, v161, s[36:37]
	s_add_i32 s22, s22, s83
	v_addc_co_u32_e64 v160, vcc, 0, v160, s[50:51]
	s_bcnt1_i32_b64 s82, s[48:49]
	s_add_i32 s22, s22, s82
	s_cmp_le_u32 s23, 20
	s_cbranch_scc1 .Ltk0_bred
	v_cmp_le_u32_e64 s[34:35], s30, v112
	v_cmp_le_u32_e64 s[36:37], s30, v113
	v_cmp_le_u32_e64 s[48:49], s30, v114
	s_bcnt1_i32_b64 s82, s[34:35]
	v_cmp_le_u32_e64 s[50:51], s30, v115
	s_add_i32 s22, s22, s82
	v_addc_co_u32_e64 v160, vcc, 0, v160, s[48:49]
	s_bcnt1_i32_b64 s83, s[36:37]
	v_cmp_le_u32_e64 s[34:35], s30, v116
	s_add_i32 s22, s22, s83
	v_cmp_le_u32_e64 s[36:37], s30, v117
	s_bcnt1_i32_b64 s82, s[50:51]
	v_cmp_le_u32_e64 s[48:49], s30, v118
	s_add_i32 s22, s22, s82
	v_cmp_le_u32_e64 s[50:51], s30, v119
	s_bcnt1_i32_b64 s83, s[34:35]
	v_addc_co_u32_e64 v161, vcc, 0, v161, s[36:37]
	s_add_i32 s22, s22, s83
	v_addc_co_u32_e64 v160, vcc, 0, v160, s[50:51]
	s_bcnt1_i32_b64 s82, s[48:49]
	s_add_i32 s22, s22, s82
	s_cmp_le_u32 s23, 22
	s_cbranch_scc1 .Ltk0_bred
	v_cmp_le_u32_e64 s[34:35], s30, v120
	v_cmp_le_u32_e64 s[36:37], s30, v121
	v_cmp_le_u32_e64 s[48:49], s30, v122
	s_bcnt1_i32_b64 s82, s[34:35]
	v_cmp_le_u32_e64 s[50:51], s30, v123
	s_add_i32 s22, s22, s82
	v_addc_co_u32_e64 v160, vcc, 0, v160, s[48:49]
	s_bcnt1_i32_b64 s83, s[36:37]
	v_cmp_le_u32_e64 s[34:35], s30, v124
	s_add_i32 s22, s22, s83
	v_cmp_le_u32_e64 s[36:37], s30, v125
	s_bcnt1_i32_b64 s82, s[50:51]
	v_cmp_le_u32_e64 s[48:49], s30, v126
	s_add_i32 s22, s22, s82
	v_cmp_le_u32_e64 s[50:51], s30, v127
	s_bcnt1_i32_b64 s83, s[34:35]
	v_addc_co_u32_e64 v161, vcc, 0, v161, s[36:37]
	s_add_i32 s22, s22, s83
	v_addc_co_u32_e64 v160, vcc, 0, v160, s[50:51]
	s_bcnt1_i32_b64 s82, s[48:49]
	s_add_i32 s22, s22, s82
	s_cmp_le_u32 s23, 24
	s_cbranch_scc1 .Ltk0_bred
	v_cmp_le_u32_e64 s[34:35], s30, v128
	v_cmp_le_u32_e64 s[36:37], s30, v129
	v_cmp_le_u32_e64 s[48:49], s30, v130
	s_bcnt1_i32_b64 s82, s[34:35]
	v_cmp_le_u32_e64 s[50:51], s30, v131
	s_add_i32 s22, s22, s82
	v_addc_co_u32_e64 v160, vcc, 0, v160, s[48:49]
	s_bcnt1_i32_b64 s83, s[36:37]
	v_cmp_le_u32_e64 s[34:35], s30, v132
	s_add_i32 s22, s22, s83
	v_cmp_le_u32_e64 s[36:37], s30, v133
	s_bcnt1_i32_b64 s82, s[50:51]
	v_cmp_le_u32_e64 s[48:49], s30, v134
	s_add_i32 s22, s22, s82
	v_cmp_le_u32_e64 s[50:51], s30, v135
	s_bcnt1_i32_b64 s83, s[34:35]
	v_addc_co_u32_e64 v161, vcc, 0, v161, s[36:37]
	s_add_i32 s22, s22, s83
	v_addc_co_u32_e64 v160, vcc, 0, v160, s[50:51]
	s_bcnt1_i32_b64 s82, s[48:49]
	s_add_i32 s22, s22, s82
	s_cmp_le_u32 s23, 26
	s_cbranch_scc1 .Ltk0_bred
	v_cmp_le_u32_e64 s[34:35], s30, v136
	v_cmp_le_u32_e64 s[36:37], s30, v137
	v_cmp_le_u32_e64 s[48:49], s30, v138
	s_bcnt1_i32_b64 s82, s[34:35]
	v_cmp_le_u32_e64 s[50:51], s30, v139
	s_add_i32 s22, s22, s82
	v_addc_co_u32_e64 v160, vcc, 0, v160, s[48:49]
	s_bcnt1_i32_b64 s83, s[36:37]
	v_cmp_le_u32_e64 s[34:35], s30, v140
	s_add_i32 s22, s22, s83
	v_cmp_le_u32_e64 s[36:37], s30, v141
	s_bcnt1_i32_b64 s82, s[50:51]
	v_cmp_le_u32_e64 s[48:49], s30, v142
	s_add_i32 s22, s22, s82
	v_cmp_le_u32_e64 s[50:51], s30, v143
	s_bcnt1_i32_b64 s83, s[34:35]
	v_addc_co_u32_e64 v161, vcc, 0, v161, s[36:37]
	s_add_i32 s22, s22, s83
	v_addc_co_u32_e64 v160, vcc, 0, v160, s[50:51]
	s_bcnt1_i32_b64 s82, s[48:49]
	s_add_i32 s22, s22, s82
	s_cmp_le_u32 s23, 28
	s_cbranch_scc1 .Ltk0_bred
	v_cmp_le_u32_e64 s[34:35], s30, v144
	v_cmp_le_u32_e64 s[36:37], s30, v145
	v_cmp_le_u32_e64 s[48:49], s30, v146
	s_bcnt1_i32_b64 s82, s[34:35]
	v_cmp_le_u32_e64 s[50:51], s30, v147
	s_add_i32 s22, s22, s82
	v_addc_co_u32_e64 v160, vcc, 0, v160, s[48:49]
	s_bcnt1_i32_b64 s83, s[36:37]
	v_cmp_le_u32_e64 s[34:35], s30, v148
	s_add_i32 s22, s22, s83
	v_cmp_le_u32_e64 s[36:37], s30, v149
	s_bcnt1_i32_b64 s82, s[50:51]
	v_cmp_le_u32_e64 s[48:49], s30, v150
	s_add_i32 s22, s22, s82
	v_cmp_le_u32_e64 s[50:51], s30, v151
	s_bcnt1_i32_b64 s83, s[34:35]
	v_addc_co_u32_e64 v161, vcc, 0, v161, s[36:37]
	s_add_i32 s22, s22, s83
	v_addc_co_u32_e64 v160, vcc, 0, v160, s[50:51]
	s_bcnt1_i32_b64 s82, s[48:49]
	s_add_i32 s22, s22, s82
	s_cmp_le_u32 s23, 30
	s_cbranch_scc1 .Ltk0_bred
	v_cmp_le_u32_e64 s[34:35], s30, v152
	v_cmp_le_u32_e64 s[36:37], s30, v153
	v_cmp_le_u32_e64 s[48:49], s30, v154
	s_bcnt1_i32_b64 s82, s[34:35]
	v_cmp_le_u32_e64 s[50:51], s30, v155
	s_add_i32 s22, s22, s82
	v_addc_co_u32_e64 v160, vcc, 0, v160, s[48:49]
	s_bcnt1_i32_b64 s83, s[36:37]
	v_cmp_le_u32_e64 s[34:35], s30, v156
	s_add_i32 s22, s22, s83
	v_cmp_le_u32_e64 s[36:37], s30, v157
	s_bcnt1_i32_b64 s82, s[50:51]
	v_cmp_le_u32_e64 s[48:49], s30, v158
	s_add_i32 s22, s22, s82
	v_cmp_le_u32_e64 s[50:51], s30, v159
	s_bcnt1_i32_b64 s83, s[34:35]
	v_addc_co_u32_e64 v161, vcc, 0, v161, s[36:37]
	s_add_i32 s22, s22, s83
	v_addc_co_u32_e64 v160, vcc, 0, v160, s[50:51]
	s_bcnt1_i32_b64 s82, s[48:49]
	s_add_i32 s22, s22, s82
.Ltk0_bred:
	v_add_u32_e32 v160, v160, v161
	s_nop 1
	v_add_u32_dpp v160, v160, v160 quad_perm:[1,0,3,2] row_mask:0xf bank_mask:0xf
	s_nop 1
	v_add_u32_dpp v160, v160, v160 quad_perm:[2,3,0,1] row_mask:0xf bank_mask:0xf
	s_nop 1
	v_add_u32_dpp v160, v160, v160 row_half_mirror row_mask:0xf bank_mask:0xf
	s_nop 1
	v_add_u32_dpp v160, v160, v160 row_mirror row_mask:0xf bank_mask:0xf
	s_nop 1
	v_readlane_b32 s31, v160, 0
	v_readlane_b32 s82, v160, 16
	v_readlane_b32 s83, v160, 32
	v_readlane_b32 s93, v160, 48
	s_nop 3
	s_add_i32 s31, s31, s82
	s_add_i32 s83, s83, s93
	s_add_i32 s31, s31, s83
	s_add_i32 s31, s31, s22
	s_cmpk_eq_u32 s31, 0x100
	s_cbranch_scc1 .Ltk0_emit
	s_cmpk_ge_u32 s31, 0x100
	s_cselect_b32 s20, s30, s20
	s_cselect_b32 s21, s21, s30
	s_branch .Ltk0_bloop
.Ltk0_exh:
	s_cmp_eq_u32 s62, 0
	s_cbranch_scc0 .Ltk0_epre
	s_mov_b32 s62, 1
	v_cmp_lt_u32_e64 s[34:35], s20, v32
	v_cmp_eq_u32_e64 s[36:37], s20, v32
	v_cmp_lt_u32_e64 s[48:49], s20, v33
	v_cmp_eq_u32_e64 s[50:51], s20, v33
	v_subrev_u32_e32 v162, 0, v169
	v_subrev_u32_e32 v163, 1, v169
	v_cndmask_b32_e64 v162, 0, v162, s[36:37]
	v_cndmask_b32_e64 v163, 0, v163, s[50:51]
	v_cndmask_b32_e64 v32, v162, -1, s[34:35]
	v_cndmask_b32_e64 v33, v163, -1, s[48:49]
	v_cmp_lt_u32_e64 s[34:35], s20, v34
	v_cmp_eq_u32_e64 s[36:37], s20, v34
	v_cmp_lt_u32_e64 s[48:49], s20, v35
	v_cmp_eq_u32_e64 s[50:51], s20, v35
	v_subrev_u32_e32 v162, 2, v169
	v_subrev_u32_e32 v163, 3, v169
	v_cndmask_b32_e64 v162, 0, v162, s[36:37]
	v_cndmask_b32_e64 v163, 0, v163, s[50:51]
	v_cndmask_b32_e64 v34, v162, -1, s[34:35]
	v_cndmask_b32_e64 v35, v163, -1, s[48:49]
	v_cmp_lt_u32_e64 s[34:35], s20, v36
	v_cmp_eq_u32_e64 s[36:37], s20, v36
	v_cmp_lt_u32_e64 s[48:49], s20, v37
	v_cmp_eq_u32_e64 s[50:51], s20, v37
	v_subrev_u32_e32 v162, 0x100, v169
	v_subrev_u32_e32 v163, 0x101, v169
	v_cndmask_b32_e64 v162, 0, v162, s[36:37]
	v_cndmask_b32_e64 v163, 0, v163, s[50:51]
	v_cndmask_b32_e64 v36, v162, -1, s[34:35]
	v_cndmask_b32_e64 v37, v163, -1, s[48:49]
	v_cmp_lt_u32_e64 s[34:35], s20, v38
	v_cmp_eq_u32_e64 s[36:37], s20, v38
	v_cmp_lt_u32_e64 s[48:49], s20, v39
	v_cmp_eq_u32_e64 s[50:51], s20, v39
	v_subrev_u32_e32 v162, 0x102, v169
	v_subrev_u32_e32 v163, 0x103, v169
	v_cndmask_b32_e64 v162, 0, v162, s[36:37]
	v_cndmask_b32_e64 v163, 0, v163, s[50:51]
	v_cndmask_b32_e64 v38, v162, -1, s[34:35]
	v_cndmask_b32_e64 v39, v163, -1, s[48:49]
	s_cmp_le_u32 s23, 2
	s_cbranch_scc1 .Ltk0_tinit
	v_cmp_lt_u32_e64 s[34:35], s20, v40
	v_cmp_eq_u32_e64 s[36:37], s20, v40
	v_cmp_lt_u32_e64 s[48:49], s20, v41
	v_cmp_eq_u32_e64 s[50:51], s20, v41
	v_subrev_u32_e32 v162, 0x200, v169
	v_subrev_u32_e32 v163, 0x201, v169
	v_cndmask_b32_e64 v162, 0, v162, s[36:37]
	v_cndmask_b32_e64 v163, 0, v163, s[50:51]
	v_cndmask_b32_e64 v40, v162, -1, s[34:35]
	v_cndmask_b32_e64 v41, v163, -1, s[48:49]
	v_cmp_lt_u32_e64 s[34:35], s20, v42
	v_cmp_eq_u32_e64 s[36:37], s20, v42
	v_cmp_lt_u32_e64 s[48:49], s20, v43
	v_cmp_eq_u32_e64 s[50:51], s20, v43
	v_subrev_u32_e32 v162, 0x202, v169
	v_subrev_u32_e32 v163, 0x203, v169
	v_cndmask_b32_e64 v162, 0, v162, s[36:37]
	v_cndmask_b32_e64 v163, 0, v163, s[50:51]
	v_cndmask_b32_e64 v42, v162, -1, s[34:35]
	v_cndmask_b32_e64 v43, v163, -1, s[48:49]
	v_cmp_lt_u32_e64 s[34:35], s20, v44
	v_cmp_eq_u32_e64 s[36:37], s20, v44
	v_cmp_lt_u32_e64 s[48:49], s20, v45
	v_cmp_eq_u32_e64 s[50:51], s20, v45
	v_subrev_u32_e32 v162, 0x300, v169
	v_subrev_u32_e32 v163, 0x301, v169
	v_cndmask_b32_e64 v162, 0, v162, s[36:37]
	v_cndmask_b32_e64 v163, 0, v163, s[50:51]
	v_cndmask_b32_e64 v44, v162, -1, s[34:35]
	v_cndmask_b32_e64 v45, v163, -1, s[48:49]
	v_cmp_lt_u32_e64 s[34:35], s20, v46
	v_cmp_eq_u32_e64 s[36:37], s20, v46
	v_cmp_lt_u32_e64 s[48:49], s20, v47
	v_cmp_eq_u32_e64 s[50:51], s20, v47
	v_subrev_u32_e32 v162, 0x302, v169
	v_subrev_u32_e32 v163, 0x303, v169
	v_cndmask_b32_e64 v162, 0, v162, s[36:37]
	v_cndmask_b32_e64 v163, 0, v163, s[50:51]
	v_cndmask_b32_e64 v46, v162, -1, s[34:35]
	v_cndmask_b32_e64 v47, v163, -1, s[48:49]
	s_cmp_le_u32 s23, 4
	s_cbranch_scc1 .Ltk0_tinit
	v_cmp_lt_u32_e64 s[34:35], s20, v48
	v_cmp_eq_u32_e64 s[36:37], s20, v48
	v_cmp_lt_u32_e64 s[48:49], s20, v49
	v_cmp_eq_u32_e64 s[50:51], s20, v49
	v_subrev_u32_e32 v162, 0x400, v169
	v_subrev_u32_e32 v163, 0x401, v169
	v_cndmask_b32_e64 v162, 0, v162, s[36:37]
	v_cndmask_b32_e64 v163, 0, v163, s[50:51]
	v_cndmask_b32_e64 v48, v162, -1, s[34:35]
	v_cndmask_b32_e64 v49, v163, -1, s[48:49]
	v_cmp_lt_u32_e64 s[34:35], s20, v50
	v_cmp_eq_u32_e64 s[36:37], s20, v50
	v_cmp_lt_u32_e64 s[48:49], s20, v51
	v_cmp_eq_u32_e64 s[50:51], s20, v51
	v_subrev_u32_e32 v162, 0x402, v169
	v_subrev_u32_e32 v163, 0x403, v169
	v_cndmask_b32_e64 v162, 0, v162, s[36:37]
	v_cndmask_b32_e64 v163, 0, v163, s[50:51]
	v_cndmask_b32_e64 v50, v162, -1, s[34:35]
	v_cndmask_b32_e64 v51, v163, -1, s[48:49]
	v_cmp_lt_u32_e64 s[34:35], s20, v52
	v_cmp_eq_u32_e64 s[36:37], s20, v52
	v_cmp_lt_u32_e64 s[48:49], s20, v53
	v_cmp_eq_u32_e64 s[50:51], s20, v53
	v_subrev_u32_e32 v162, 0x500, v169
	v_subrev_u32_e32 v163, 0x501, v169
	v_cndmask_b32_e64 v162, 0, v162, s[36:37]
	v_cndmask_b32_e64 v163, 0, v163, s[50:51]
	v_cndmask_b32_e64 v52, v162, -1, s[34:35]
	v_cndmask_b32_e64 v53, v163, -1, s[48:49]
	v_cmp_lt_u32_e64 s[34:35], s20, v54
	v_cmp_eq_u32_e64 s[36:37], s20, v54
	v_cmp_lt_u32_e64 s[48:49], s20, v55
	v_cmp_eq_u32_e64 s[50:51], s20, v55
	v_subrev_u32_e32 v162, 0x502, v169
	v_subrev_u32_e32 v163, 0x503, v169
	v_cndmask_b32_e64 v162, 0, v162, s[36:37]
	v_cndmask_b32_e64 v163, 0, v163, s[50:51]
	v_cndmask_b32_e64 v54, v162, -1, s[34:35]
	v_cndmask_b32_e64 v55, v163, -1, s[48:49]
	s_cmp_le_u32 s23, 6
	s_cbranch_scc1 .Ltk0_tinit
	v_cmp_lt_u32_e64 s[34:35], s20, v56
	v_cmp_eq_u32_e64 s[36:37], s20, v56
	v_cmp_lt_u32_e64 s[48:49], s20, v57
	v_cmp_eq_u32_e64 s[50:51], s20, v57
	v_subrev_u32_e32 v162, 0x600, v169
	v_subrev_u32_e32 v163, 0x601, v169
	v_cndmask_b32_e64 v162, 0, v162, s[36:37]
	v_cndmask_b32_e64 v163, 0, v163, s[50:51]
	v_cndmask_b32_e64 v56, v162, -1, s[34:35]
	v_cndmask_b32_e64 v57, v163, -1, s[48:49]
	v_cmp_lt_u32_e64 s[34:35], s20, v58
	v_cmp_eq_u32_e64 s[36:37], s20, v58
	v_cmp_lt_u32_e64 s[48:49], s20, v59
	v_cmp_eq_u32_e64 s[50:51], s20, v59
	v_subrev_u32_e32 v162, 0x602, v169
	v_subrev_u32_e32 v163, 0x603, v169
	v_cndmask_b32_e64 v162, 0, v162, s[36:37]
	v_cndmask_b32_e64 v163, 0, v163, s[50:51]
	v_cndmask_b32_e64 v58, v162, -1, s[34:35]
	v_cndmask_b32_e64 v59, v163, -1, s[48:49]
	v_cmp_lt_u32_e64 s[34:35], s20, v60
	v_cmp_eq_u32_e64 s[36:37], s20, v60
	v_cmp_lt_u32_e64 s[48:49], s20, v61
	v_cmp_eq_u32_e64 s[50:51], s20, v61
	v_subrev_u32_e32 v162, 0x700, v169
	v_subrev_u32_e32 v163, 0x701, v169
	v_cndmask_b32_e64 v162, 0, v162, s[36:37]
	v_cndmask_b32_e64 v163, 0, v163, s[50:51]
	v_cndmask_b32_e64 v60, v162, -1, s[34:35]
	v_cndmask_b32_e64 v61, v163, -1, s[48:49]
	v_cmp_lt_u32_e64 s[34:35], s20, v62
	v_cmp_eq_u32_e64 s[36:37], s20, v62
	v_cmp_lt_u32_e64 s[48:49], s20, v63
	v_cmp_eq_u32_e64 s[50:51], s20, v63
	v_subrev_u32_e32 v162, 0x702, v169
	v_subrev_u32_e32 v163, 0x703, v169
	v_cndmask_b32_e64 v162, 0, v162, s[36:37]
	v_cndmask_b32_e64 v163, 0, v163, s[50:51]
	v_cndmask_b32_e64 v62, v162, -1, s[34:35]
	v_cndmask_b32_e64 v63, v163, -1, s[48:49]
	s_cmp_le_u32 s23, 8
	s_cbranch_scc1 .Ltk0_tinit
	v_cmp_lt_u32_e64 s[34:35], s20, v64
	v_cmp_eq_u32_e64 s[36:37], s20, v64
	v_cmp_lt_u32_e64 s[48:49], s20, v65
	v_cmp_eq_u32_e64 s[50:51], s20, v65
	v_subrev_u32_e32 v162, 0x800, v169
	v_subrev_u32_e32 v163, 0x801, v169
	v_cndmask_b32_e64 v162, 0, v162, s[36:37]
	v_cndmask_b32_e64 v163, 0, v163, s[50:51]
	v_cndmask_b32_e64 v64, v162, -1, s[34:35]
	v_cndmask_b32_e64 v65, v163, -1, s[48:49]
	v_cmp_lt_u32_e64 s[34:35], s20, v66
	v_cmp_eq_u32_e64 s[36:37], s20, v66
	v_cmp_lt_u32_e64 s[48:49], s20, v67
	v_cmp_eq_u32_e64 s[50:51], s20, v67
	v_subrev_u32_e32 v162, 0x802, v169
	v_subrev_u32_e32 v163, 0x803, v169
	v_cndmask_b32_e64 v162, 0, v162, s[36:37]
	v_cndmask_b32_e64 v163, 0, v163, s[50:51]
	v_cndmask_b32_e64 v66, v162, -1, s[34:35]
	v_cndmask_b32_e64 v67, v163, -1, s[48:49]
	v_cmp_lt_u32_e64 s[34:35], s20, v68
	v_cmp_eq_u32_e64 s[36:37], s20, v68
	v_cmp_lt_u32_e64 s[48:49], s20, v69
	v_cmp_eq_u32_e64 s[50:51], s20, v69
	v_subrev_u32_e32 v162, 0x900, v169
	v_subrev_u32_e32 v163, 0x901, v169
	v_cndmask_b32_e64 v162, 0, v162, s[36:37]
	v_cndmask_b32_e64 v163, 0, v163, s[50:51]
	v_cndmask_b32_e64 v68, v162, -1, s[34:35]
	v_cndmask_b32_e64 v69, v163, -1, s[48:49]
	v_cmp_lt_u32_e64 s[34:35], s20, v70
	v_cmp_eq_u32_e64 s[36:37], s20, v70
	v_cmp_lt_u32_e64 s[48:49], s20, v71
	v_cmp_eq_u32_e64 s[50:51], s20, v71
	v_subrev_u32_e32 v162, 0x902, v169
	v_subrev_u32_e32 v163, 0x903, v169
	v_cndmask_b32_e64 v162, 0, v162, s[36:37]
	v_cndmask_b32_e64 v163, 0, v163, s[50:51]
	v_cndmask_b32_e64 v70, v162, -1, s[34:35]
	v_cndmask_b32_e64 v71, v163, -1, s[48:49]
	s_cmp_le_u32 s23, 10
	s_cbranch_scc1 .Ltk0_tinit
	v_cmp_lt_u32_e64 s[34:35], s20, v72
	v_cmp_eq_u32_e64 s[36:37], s20, v72
	v_cmp_lt_u32_e64 s[48:49], s20, v73
	v_cmp_eq_u32_e64 s[50:51], s20, v73
	v_subrev_u32_e32 v162, 0xa00, v169
	v_subrev_u32_e32 v163, 0xa01, v169
	v_cndmask_b32_e64 v162, 0, v162, s[36:37]
	v_cndmask_b32_e64 v163, 0, v163, s[50:51]
	v_cndmask_b32_e64 v72, v162, -1, s[34:35]
	v_cndmask_b32_e64 v73, v163, -1, s[48:49]
	v_cmp_lt_u32_e64 s[34:35], s20, v74
	v_cmp_eq_u32_e64 s[36:37], s20, v74
	v_cmp_lt_u32_e64 s[48:49], s20, v75
	v_cmp_eq_u32_e64 s[50:51], s20, v75
	v_subrev_u32_e32 v162, 0xa02, v169
	v_subrev_u32_e32 v163, 0xa03, v169
	v_cndmask_b32_e64 v162, 0, v162, s[36:37]
	v_cndmask_b32_e64 v163, 0, v163, s[50:51]
	v_cndmask_b32_e64 v74, v162, -1, s[34:35]
	v_cndmask_b32_e64 v75, v163, -1, s[48:49]
	v_cmp_lt_u32_e64 s[34:35], s20, v76
	v_cmp_eq_u32_e64 s[36:37], s20, v76
	v_cmp_lt_u32_e64 s[48:49], s20, v77
	v_cmp_eq_u32_e64 s[50:51], s20, v77
	v_subrev_u32_e32 v162, 0xb00, v169
	v_subrev_u32_e32 v163, 0xb01, v169
	v_cndmask_b32_e64 v162, 0, v162, s[36:37]
	v_cndmask_b32_e64 v163, 0, v163, s[50:51]
	v_cndmask_b32_e64 v76, v162, -1, s[34:35]
	v_cndmask_b32_e64 v77, v163, -1, s[48:49]
	v_cmp_lt_u32_e64 s[34:35], s20, v78
	v_cmp_eq_u32_e64 s[36:37], s20, v78
	v_cmp_lt_u32_e64 s[48:49], s20, v79
	v_cmp_eq_u32_e64 s[50:51], s20, v79
	v_subrev_u32_e32 v162, 0xb02, v169
	v_subrev_u32_e32 v163, 0xb03, v169
	v_cndmask_b32_e64 v162, 0, v162, s[36:37]
	v_cndmask_b32_e64 v163, 0, v163, s[50:51]
	v_cndmask_b32_e64 v78, v162, -1, s[34:35]
	v_cndmask_b32_e64 v79, v163, -1, s[48:49]
	s_cmp_le_u32 s23, 12
	s_cbranch_scc1 .Ltk0_tinit
	v_cmp_lt_u32_e64 s[34:35], s20, v80
	v_cmp_eq_u32_e64 s[36:37], s20, v80
	v_cmp_lt_u32_e64 s[48:49], s20, v81
	v_cmp_eq_u32_e64 s[50:51], s20, v81
	v_subrev_u32_e32 v162, 0xc00, v169
	v_subrev_u32_e32 v163, 0xc01, v169
	v_cndmask_b32_e64 v162, 0, v162, s[36:37]
	v_cndmask_b32_e64 v163, 0, v163, s[50:51]
	v_cndmask_b32_e64 v80, v162, -1, s[34:35]
	v_cndmask_b32_e64 v81, v163, -1, s[48:49]
	v_cmp_lt_u32_e64 s[34:35], s20, v82
	v_cmp_eq_u32_e64 s[36:37], s20, v82
	v_cmp_lt_u32_e64 s[48:49], s20, v83
	v_cmp_eq_u32_e64 s[50:51], s20, v83
	v_subrev_u32_e32 v162, 0xc02, v169
	v_subrev_u32_e32 v163, 0xc03, v169
	v_cndmask_b32_e64 v162, 0, v162, s[36:37]
	v_cndmask_b32_e64 v163, 0, v163, s[50:51]
	v_cndmask_b32_e64 v82, v162, -1, s[34:35]
	v_cndmask_b32_e64 v83, v163, -1, s[48:49]
	v_cmp_lt_u32_e64 s[34:35], s20, v84
	v_cmp_eq_u32_e64 s[36:37], s20, v84
	v_cmp_lt_u32_e64 s[48:49], s20, v85
	v_cmp_eq_u32_e64 s[50:51], s20, v85
	v_subrev_u32_e32 v162, 0xd00, v169
	v_subrev_u32_e32 v163, 0xd01, v169
	v_cndmask_b32_e64 v162, 0, v162, s[36:37]
	v_cndmask_b32_e64 v163, 0, v163, s[50:51]
	v_cndmask_b32_e64 v84, v162, -1, s[34:35]
	v_cndmask_b32_e64 v85, v163, -1, s[48:49]
	v_cmp_lt_u32_e64 s[34:35], s20, v86
	v_cmp_eq_u32_e64 s[36:37], s20, v86
	v_cmp_lt_u32_e64 s[48:49], s20, v87
	v_cmp_eq_u32_e64 s[50:51], s20, v87
	v_subrev_u32_e32 v162, 0xd02, v169
	v_subrev_u32_e32 v163, 0xd03, v169
	v_cndmask_b32_e64 v162, 0, v162, s[36:37]
	v_cndmask_b32_e64 v163, 0, v163, s[50:51]
	v_cndmask_b32_e64 v86, v162, -1, s[34:35]
	v_cndmask_b32_e64 v87, v163, -1, s[48:49]
	s_cmp_le_u32 s23, 14
	s_cbranch_scc1 .Ltk0_tinit
	v_cmp_lt_u32_e64 s[34:35], s20, v88
	v_cmp_eq_u32_e64 s[36:37], s20, v88
	v_cmp_lt_u32_e64 s[48:49], s20, v89
	v_cmp_eq_u32_e64 s[50:51], s20, v89
	v_subrev_u32_e32 v162, 0xe00, v169
	v_subrev_u32_e32 v163, 0xe01, v169
	v_cndmask_b32_e64 v162, 0, v162, s[36:37]
	v_cndmask_b32_e64 v163, 0, v163, s[50:51]
	v_cndmask_b32_e64 v88, v162, -1, s[34:35]
	v_cndmask_b32_e64 v89, v163, -1, s[48:49]
	v_cmp_lt_u32_e64 s[34:35], s20, v90
	v_cmp_eq_u32_e64 s[36:37], s20, v90
	v_cmp_lt_u32_e64 s[48:49], s20, v91
	v_cmp_eq_u32_e64 s[50:51], s20, v91
	v_subrev_u32_e32 v162, 0xe02, v169
	v_subrev_u32_e32 v163, 0xe03, v169
	v_cndmask_b32_e64 v162, 0, v162, s[36:37]
	v_cndmask_b32_e64 v163, 0, v163, s[50:51]
	v_cndmask_b32_e64 v90, v162, -1, s[34:35]
	v_cndmask_b32_e64 v91, v163, -1, s[48:49]
	v_cmp_lt_u32_e64 s[34:35], s20, v92
	v_cmp_eq_u32_e64 s[36:37], s20, v92
	v_cmp_lt_u32_e64 s[48:49], s20, v93
	v_cmp_eq_u32_e64 s[50:51], s20, v93
	v_subrev_u32_e32 v162, 0xf00, v169
	v_subrev_u32_e32 v163, 0xf01, v169
	v_cndmask_b32_e64 v162, 0, v162, s[36:37]
	v_cndmask_b32_e64 v163, 0, v163, s[50:51]
	v_cndmask_b32_e64 v92, v162, -1, s[34:35]
	v_cndmask_b32_e64 v93, v163, -1, s[48:49]
	v_cmp_lt_u32_e64 s[34:35], s20, v94
	v_cmp_eq_u32_e64 s[36:37], s20, v94
	v_cmp_lt_u32_e64 s[48:49], s20, v95
	v_cmp_eq_u32_e64 s[50:51], s20, v95
	v_subrev_u32_e32 v162, 0xf02, v169
	v_subrev_u32_e32 v163, 0xf03, v169
	v_cndmask_b32_e64 v162, 0, v162, s[36:37]
	v_cndmask_b32_e64 v163, 0, v163, s[50:51]
	v_cndmask_b32_e64 v94, v162, -1, s[34:35]
	v_cndmask_b32_e64 v95, v163, -1, s[48:49]
	s_cmp_le_u32 s23, 16
	s_cbranch_scc1 .Ltk0_tinit
	v_cmp_lt_u32_e64 s[34:35], s20, v96
	v_cmp_eq_u32_e64 s[36:37], s20, v96
	v_cmp_lt_u32_e64 s[48:49], s20, v97
	v_cmp_eq_u32_e64 s[50:51], s20, v97
	v_subrev_u32_e32 v162, 0x1000, v169
	v_subrev_u32_e32 v163, 0x1001, v169
	v_cndmask_b32_e64 v162, 0, v162, s[36:37]
	v_cndmask_b32_e64 v163, 0, v163, s[50:51]
	v_cndmask_b32_e64 v96, v162, -1, s[34:35]
	v_cndmask_b32_e64 v97, v163, -1, s[48:49]
	v_cmp_lt_u32_e64 s[34:35], s20, v98
	v_cmp_eq_u32_e64 s[36:37], s20, v98
	v_cmp_lt_u32_e64 s[48:49], s20, v99
	v_cmp_eq_u32_e64 s[50:51], s20, v99
	v_subrev_u32_e32 v162, 0x1002, v169
	v_subrev_u32_e32 v163, 0x1003, v169
	v_cndmask_b32_e64 v162, 0, v162, s[36:37]
	v_cndmask_b32_e64 v163, 0, v163, s[50:51]
	v_cndmask_b32_e64 v98, v162, -1, s[34:35]
	v_cndmask_b32_e64 v99, v163, -1, s[48:49]
	v_cmp_lt_u32_e64 s[34:35], s20, v100
	v_cmp_eq_u32_e64 s[36:37], s20, v100
	v_cmp_lt_u32_e64 s[48:49], s20, v101
	v_cmp_eq_u32_e64 s[50:51], s20, v101
	v_subrev_u32_e32 v162, 0x1100, v169
	v_subrev_u32_e32 v163, 0x1101, v169
	v_cndmask_b32_e64 v162, 0, v162, s[36:37]
	v_cndmask_b32_e64 v163, 0, v163, s[50:51]
	v_cndmask_b32_e64 v100, v162, -1, s[34:35]
	v_cndmask_b32_e64 v101, v163, -1, s[48:49]
	v_cmp_lt_u32_e64 s[34:35], s20, v102
	v_cmp_eq_u32_e64 s[36:37], s20, v102
	v_cmp_lt_u32_e64 s[48:49], s20, v103
	v_cmp_eq_u32_e64 s[50:51], s20, v103
	v_subrev_u32_e32 v162, 0x1102, v169
	v_subrev_u32_e32 v163, 0x1103, v169
	v_cndmask_b32_e64 v162, 0, v162, s[36:37]
	v_cndmask_b32_e64 v163, 0, v163, s[50:51]
	v_cndmask_b32_e64 v102, v162, -1, s[34:35]
	v_cndmask_b32_e64 v103, v163, -1, s[48:49]
	s_cmp_le_u32 s23, 18
	s_cbranch_scc1 .Ltk0_tinit
	v_cmp_lt_u32_e64 s[34:35], s20, v104
	v_cmp_eq_u32_e64 s[36:37], s20, v104
	v_cmp_lt_u32_e64 s[48:49], s20, v105
	v_cmp_eq_u32_e64 s[50:51], s20, v105
	v_subrev_u32_e32 v162, 0x1200, v169
	v_subrev_u32_e32 v163, 0x1201, v169
	v_cndmask_b32_e64 v162, 0, v162, s[36:37]
	v_cndmask_b32_e64 v163, 0, v163, s[50:51]
	v_cndmask_b32_e64 v104, v162, -1, s[34:35]
	v_cndmask_b32_e64 v105, v163, -1, s[48:49]
	v_cmp_lt_u32_e64 s[34:35], s20, v106
	v_cmp_eq_u32_e64 s[36:37], s20, v106
	v_cmp_lt_u32_e64 s[48:49], s20, v107
	v_cmp_eq_u32_e64 s[50:51], s20, v107
	v_subrev_u32_e32 v162, 0x1202, v169
	v_subrev_u32_e32 v163, 0x1203, v169
	v_cndmask_b32_e64 v162, 0, v162, s[36:37]
	v_cndmask_b32_e64 v163, 0, v163, s[50:51]
	v_cndmask_b32_e64 v106, v162, -1, s[34:35]
	v_cndmask_b32_e64 v107, v163, -1, s[48:49]
	v_cmp_lt_u32_e64 s[34:35], s20, v108
	v_cmp_eq_u32_e64 s[36:37], s20, v108
	v_cmp_lt_u32_e64 s[48:49], s20, v109
	v_cmp_eq_u32_e64 s[50:51], s20, v109
	v_subrev_u32_e32 v162, 0x1300, v169
	v_subrev_u32_e32 v163, 0x1301, v169
	v_cndmask_b32_e64 v162, 0, v162, s[36:37]
	v_cndmask_b32_e64 v163, 0, v163, s[50:51]
	v_cndmask_b32_e64 v108, v162, -1, s[34:35]
	v_cndmask_b32_e64 v109, v163, -1, s[48:49]
	v_cmp_lt_u32_e64 s[34:35], s20, v110
	v_cmp_eq_u32_e64 s[36:37], s20, v110
	v_cmp_lt_u32_e64 s[48:49], s20, v111
	v_cmp_eq_u32_e64 s[50:51], s20, v111
	v_subrev_u32_e32 v162, 0x1302, v169
	v_subrev_u32_e32 v163, 0x1303, v169
	v_cndmask_b32_e64 v162, 0, v162, s[36:37]
	v_cndmask_b32_e64 v163, 0, v163, s[50:51]
	v_cndmask_b32_e64 v110, v162, -1, s[34:35]
	v_cndmask_b32_e64 v111, v163, -1, s[48:49]
	s_cmp_le_u32 s23, 20
	s_cbranch_scc1 .Ltk0_tinit
	v_cmp_lt_u32_e64 s[34:35], s20, v112
	v_cmp_eq_u32_e64 s[36:37], s20, v112
	v_cmp_lt_u32_e64 s[48:49], s20, v113
	v_cmp_eq_u32_e64 s[50:51], s20, v113
	v_subrev_u32_e32 v162, 0x1400, v169
	v_subrev_u32_e32 v163, 0x1401, v169
	v_cndmask_b32_e64 v162, 0, v162, s[36:37]
	v_cndmask_b32_e64 v163, 0, v163, s[50:51]
	v_cndmask_b32_e64 v112, v162, -1, s[34:35]
	v_cndmask_b32_e64 v113, v163, -1, s[48:49]
	v_cmp_lt_u32_e64 s[34:35], s20, v114
	v_cmp_eq_u32_e64 s[36:37], s20, v114
	v_cmp_lt_u32_e64 s[48:49], s20, v115
	v_cmp_eq_u32_e64 s[50:51], s20, v115
	v_subrev_u32_e32 v162, 0x1402, v169
	v_subrev_u32_e32 v163, 0x1403, v169
	v_cndmask_b32_e64 v162, 0, v162, s[36:37]
	v_cndmask_b32_e64 v163, 0, v163, s[50:51]
	v_cndmask_b32_e64 v114, v162, -1, s[34:35]
	v_cndmask_b32_e64 v115, v163, -1, s[48:49]
	v_cmp_lt_u32_e64 s[34:35], s20, v116
	v_cmp_eq_u32_e64 s[36:37], s20, v116
	v_cmp_lt_u32_e64 s[48:49], s20, v117
	v_cmp_eq_u32_e64 s[50:51], s20, v117
	v_subrev_u32_e32 v162, 0x1500, v169
	v_subrev_u32_e32 v163, 0x1501, v169
	v_cndmask_b32_e64 v162, 0, v162, s[36:37]
	v_cndmask_b32_e64 v163, 0, v163, s[50:51]
	v_cndmask_b32_e64 v116, v162, -1, s[34:35]
	v_cndmask_b32_e64 v117, v163, -1, s[48:49]
	v_cmp_lt_u32_e64 s[34:35], s20, v118
	v_cmp_eq_u32_e64 s[36:37], s20, v118
	v_cmp_lt_u32_e64 s[48:49], s20, v119
	v_cmp_eq_u32_e64 s[50:51], s20, v119
	v_subrev_u32_e32 v162, 0x1502, v169
	v_subrev_u32_e32 v163, 0x1503, v169
	v_cndmask_b32_e64 v162, 0, v162, s[36:37]
	v_cndmask_b32_e64 v163, 0, v163, s[50:51]
	v_cndmask_b32_e64 v118, v162, -1, s[34:35]
	v_cndmask_b32_e64 v119, v163, -1, s[48:49]
	s_cmp_le_u32 s23, 22
	s_cbranch_scc1 .Ltk0_tinit
	v_cmp_lt_u32_e64 s[34:35], s20, v120
	v_cmp_eq_u32_e64 s[36:37], s20, v120
	v_cmp_lt_u32_e64 s[48:49], s20, v121
	v_cmp_eq_u32_e64 s[50:51], s20, v121
	v_subrev_u32_e32 v162, 0x1600, v169
	v_subrev_u32_e32 v163, 0x1601, v169
	v_cndmask_b32_e64 v162, 0, v162, s[36:37]
	v_cndmask_b32_e64 v163, 0, v163, s[50:51]
	v_cndmask_b32_e64 v120, v162, -1, s[34:35]
	v_cndmask_b32_e64 v121, v163, -1, s[48:49]
	v_cmp_lt_u32_e64 s[34:35], s20, v122
	v_cmp_eq_u32_e64 s[36:37], s20, v122
	v_cmp_lt_u32_e64 s[48:49], s20, v123
	v_cmp_eq_u32_e64 s[50:51], s20, v123
	v_subrev_u32_e32 v162, 0x1602, v169
	v_subrev_u32_e32 v163, 0x1603, v169
	v_cndmask_b32_e64 v162, 0, v162, s[36:37]
	v_cndmask_b32_e64 v163, 0, v163, s[50:51]
	v_cndmask_b32_e64 v122, v162, -1, s[34:35]
	v_cndmask_b32_e64 v123, v163, -1, s[48:49]
	v_cmp_lt_u32_e64 s[34:35], s20, v124
	v_cmp_eq_u32_e64 s[36:37], s20, v124
	v_cmp_lt_u32_e64 s[48:49], s20, v125
	v_cmp_eq_u32_e64 s[50:51], s20, v125
	v_subrev_u32_e32 v162, 0x1700, v169
	v_subrev_u32_e32 v163, 0x1701, v169
	v_cndmask_b32_e64 v162, 0, v162, s[36:37]
	v_cndmask_b32_e64 v163, 0, v163, s[50:51]
	v_cndmask_b32_e64 v124, v162, -1, s[34:35]
	v_cndmask_b32_e64 v125, v163, -1, s[48:49]
	v_cmp_lt_u32_e64 s[34:35], s20, v126
	v_cmp_eq_u32_e64 s[36:37], s20, v126
	v_cmp_lt_u32_e64 s[48:49], s20, v127
	v_cmp_eq_u32_e64 s[50:51], s20, v127
	v_subrev_u32_e32 v162, 0x1702, v169
	v_subrev_u32_e32 v163, 0x1703, v169
	v_cndmask_b32_e64 v162, 0, v162, s[36:37]
	v_cndmask_b32_e64 v163, 0, v163, s[50:51]
	v_cndmask_b32_e64 v126, v162, -1, s[34:35]
	v_cndmask_b32_e64 v127, v163, -1, s[48:49]
	s_cmp_le_u32 s23, 24
	s_cbranch_scc1 .Ltk0_tinit
	v_cmp_lt_u32_e64 s[34:35], s20, v128
	v_cmp_eq_u32_e64 s[36:37], s20, v128
	v_cmp_lt_u32_e64 s[48:49], s20, v129
	v_cmp_eq_u32_e64 s[50:51], s20, v129
	v_subrev_u32_e32 v162, 0x1800, v169
	v_subrev_u32_e32 v163, 0x1801, v169
	v_cndmask_b32_e64 v162, 0, v162, s[36:37]
	v_cndmask_b32_e64 v163, 0, v163, s[50:51]
	v_cndmask_b32_e64 v128, v162, -1, s[34:35]
	v_cndmask_b32_e64 v129, v163, -1, s[48:49]
	v_cmp_lt_u32_e64 s[34:35], s20, v130
	v_cmp_eq_u32_e64 s[36:37], s20, v130
	v_cmp_lt_u32_e64 s[48:49], s20, v131
	v_cmp_eq_u32_e64 s[50:51], s20, v131
	v_subrev_u32_e32 v162, 0x1802, v169
	v_subrev_u32_e32 v163, 0x1803, v169
	v_cndmask_b32_e64 v162, 0, v162, s[36:37]
	v_cndmask_b32_e64 v163, 0, v163, s[50:51]
	v_cndmask_b32_e64 v130, v162, -1, s[34:35]
	v_cndmask_b32_e64 v131, v163, -1, s[48:49]
	v_cmp_lt_u32_e64 s[34:35], s20, v132
	v_cmp_eq_u32_e64 s[36:37], s20, v132
	v_cmp_lt_u32_e64 s[48:49], s20, v133
	v_cmp_eq_u32_e64 s[50:51], s20, v133
	v_subrev_u32_e32 v162, 0x1900, v169
	v_subrev_u32_e32 v163, 0x1901, v169
	v_cndmask_b32_e64 v162, 0, v162, s[36:37]
	v_cndmask_b32_e64 v163, 0, v163, s[50:51]
	v_cndmask_b32_e64 v132, v162, -1, s[34:35]
	v_cndmask_b32_e64 v133, v163, -1, s[48:49]
	v_cmp_lt_u32_e64 s[34:35], s20, v134
	v_cmp_eq_u32_e64 s[36:37], s20, v134
	v_cmp_lt_u32_e64 s[48:49], s20, v135
	v_cmp_eq_u32_e64 s[50:51], s20, v135
	v_subrev_u32_e32 v162, 0x1902, v169
	v_subrev_u32_e32 v163, 0x1903, v169
	v_cndmask_b32_e64 v162, 0, v162, s[36:37]
	v_cndmask_b32_e64 v163, 0, v163, s[50:51]
	v_cndmask_b32_e64 v134, v162, -1, s[34:35]
	v_cndmask_b32_e64 v135, v163, -1, s[48:49]
	s_cmp_le_u32 s23, 26
	s_cbranch_scc1 .Ltk0_tinit
	v_cmp_lt_u32_e64 s[34:35], s20, v136
	v_cmp_eq_u32_e64 s[36:37], s20, v136
	v_cmp_lt_u32_e64 s[48:49], s20, v137
	v_cmp_eq_u32_e64 s[50:51], s20, v137
	v_subrev_u32_e32 v162, 0x1a00, v169
	v_subrev_u32_e32 v163, 0x1a01, v169
	v_cndmask_b32_e64 v162, 0, v162, s[36:37]
	v_cndmask_b32_e64 v163, 0, v163, s[50:51]
	v_cndmask_b32_e64 v136, v162, -1, s[34:35]
	v_cndmask_b32_e64 v137, v163, -1, s[48:49]
	v_cmp_lt_u32_e64 s[34:35], s20, v138
	v_cmp_eq_u32_e64 s[36:37], s20, v138
	v_cmp_lt_u32_e64 s[48:49], s20, v139
	v_cmp_eq_u32_e64 s[50:51], s20, v139
	v_subrev_u32_e32 v162, 0x1a02, v169
	v_subrev_u32_e32 v163, 0x1a03, v169
	v_cndmask_b32_e64 v162, 0, v162, s[36:37]
	v_cndmask_b32_e64 v163, 0, v163, s[50:51]
	v_cndmask_b32_e64 v138, v162, -1, s[34:35]
	v_cndmask_b32_e64 v139, v163, -1, s[48:49]
	v_cmp_lt_u32_e64 s[34:35], s20, v140
	v_cmp_eq_u32_e64 s[36:37], s20, v140
	v_cmp_lt_u32_e64 s[48:49], s20, v141
	v_cmp_eq_u32_e64 s[50:51], s20, v141
	v_subrev_u32_e32 v162, 0x1b00, v169
	v_subrev_u32_e32 v163, 0x1b01, v169
	v_cndmask_b32_e64 v162, 0, v162, s[36:37]
	v_cndmask_b32_e64 v163, 0, v163, s[50:51]
	v_cndmask_b32_e64 v140, v162, -1, s[34:35]
	v_cndmask_b32_e64 v141, v163, -1, s[48:49]
	v_cmp_lt_u32_e64 s[34:35], s20, v142
	v_cmp_eq_u32_e64 s[36:37], s20, v142
	v_cmp_lt_u32_e64 s[48:49], s20, v143
	v_cmp_eq_u32_e64 s[50:51], s20, v143
	v_subrev_u32_e32 v162, 0x1b02, v169
	v_subrev_u32_e32 v163, 0x1b03, v169
	v_cndmask_b32_e64 v162, 0, v162, s[36:37]
	v_cndmask_b32_e64 v163, 0, v163, s[50:51]
	v_cndmask_b32_e64 v142, v162, -1, s[34:35]
	v_cndmask_b32_e64 v143, v163, -1, s[48:49]
	s_cmp_le_u32 s23, 28
	s_cbranch_scc1 .Ltk0_tinit
	v_cmp_lt_u32_e64 s[34:35], s20, v144
	v_cmp_eq_u32_e64 s[36:37], s20, v144
	v_cmp_lt_u32_e64 s[48:49], s20, v145
	v_cmp_eq_u32_e64 s[50:51], s20, v145
	v_subrev_u32_e32 v162, 0x1c00, v169
	v_subrev_u32_e32 v163, 0x1c01, v169
	v_cndmask_b32_e64 v162, 0, v162, s[36:37]
	v_cndmask_b32_e64 v163, 0, v163, s[50:51]
	v_cndmask_b32_e64 v144, v162, -1, s[34:35]
	v_cndmask_b32_e64 v145, v163, -1, s[48:49]
	v_cmp_lt_u32_e64 s[34:35], s20, v146
	v_cmp_eq_u32_e64 s[36:37], s20, v146
	v_cmp_lt_u32_e64 s[48:49], s20, v147
	v_cmp_eq_u32_e64 s[50:51], s20, v147
	v_subrev_u32_e32 v162, 0x1c02, v169
	v_subrev_u32_e32 v163, 0x1c03, v169
	v_cndmask_b32_e64 v162, 0, v162, s[36:37]
	v_cndmask_b32_e64 v163, 0, v163, s[50:51]
	v_cndmask_b32_e64 v146, v162, -1, s[34:35]
	v_cndmask_b32_e64 v147, v163, -1, s[48:49]
	v_cmp_lt_u32_e64 s[34:35], s20, v148
	v_cmp_eq_u32_e64 s[36:37], s20, v148
	v_cmp_lt_u32_e64 s[48:49], s20, v149
	v_cmp_eq_u32_e64 s[50:51], s20, v149
	v_subrev_u32_e32 v162, 0x1d00, v169
	v_subrev_u32_e32 v163, 0x1d01, v169
	v_cndmask_b32_e64 v162, 0, v162, s[36:37]
	v_cndmask_b32_e64 v163, 0, v163, s[50:51]
	v_cndmask_b32_e64 v148, v162, -1, s[34:35]
	v_cndmask_b32_e64 v149, v163, -1, s[48:49]
	v_cmp_lt_u32_e64 s[34:35], s20, v150
	v_cmp_eq_u32_e64 s[36:37], s20, v150
	v_cmp_lt_u32_e64 s[48:49], s20, v151
	v_cmp_eq_u32_e64 s[50:51], s20, v151
	v_subrev_u32_e32 v162, 0x1d02, v169
	v_subrev_u32_e32 v163, 0x1d03, v169
	v_cndmask_b32_e64 v162, 0, v162, s[36:37]
	v_cndmask_b32_e64 v163, 0, v163, s[50:51]
	v_cndmask_b32_e64 v150, v162, -1, s[34:35]
	v_cndmask_b32_e64 v151, v163, -1, s[48:49]
	s_cmp_le_u32 s23, 30
	s_cbranch_scc1 .Ltk0_tinit
	v_cmp_lt_u32_e64 s[34:35], s20, v152
	v_cmp_eq_u32_e64 s[36:37], s20, v152
	v_cmp_lt_u32_e64 s[48:49], s20, v153
	v_cmp_eq_u32_e64 s[50:51], s20, v153
	v_subrev_u32_e32 v162, 0x1e00, v169
	v_subrev_u32_e32 v163, 0x1e01, v169
	v_cndmask_b32_e64 v162, 0, v162, s[36:37]
	v_cndmask_b32_e64 v163, 0, v163, s[50:51]
	v_cndmask_b32_e64 v152, v162, -1, s[34:35]
	v_cndmask_b32_e64 v153, v163, -1, s[48:49]
	v_cmp_lt_u32_e64 s[34:35], s20, v154
	v_cmp_eq_u32_e64 s[36:37], s20, v154
	v_cmp_lt_u32_e64 s[48:49], s20, v155
	v_cmp_eq_u32_e64 s[50:51], s20, v155
	v_subrev_u32_e32 v162, 0x1e02, v169
	v_subrev_u32_e32 v163, 0x1e03, v169
	v_cndmask_b32_e64 v162, 0, v162, s[36:37]
	v_cndmask_b32_e64 v163, 0, v163, s[50:51]
	v_cndmask_b32_e64 v154, v162, -1, s[34:35]
	v_cndmask_b32_e64 v155, v163, -1, s[48:49]
	v_cmp_lt_u32_e64 s[34:35], s20, v156
	v_cmp_eq_u32_e64 s[36:37], s20, v156
	v_cmp_lt_u32_e64 s[48:49], s20, v157
	v_cmp_eq_u32_e64 s[50:51], s20, v157
	v_subrev_u32_e32 v162, 0x1f00, v169
	v_subrev_u32_e32 v163, 0x1f01, v169
	v_cndmask_b32_e64 v162, 0, v162, s[36:37]
	v_cndmask_b32_e64 v163, 0, v163, s[50:51]
	v_cndmask_b32_e64 v156, v162, -1, s[34:35]
	v_cndmask_b32_e64 v157, v163, -1, s[48:49]
	v_cmp_lt_u32_e64 s[34:35], s20, v158
	v_cmp_eq_u32_e64 s[36:37], s20, v158
	v_cmp_lt_u32_e64 s[48:49], s20, v159
	v_cmp_eq_u32_e64 s[50:51], s20, v159
	v_subrev_u32_e32 v162, 0x1f02, v169
	v_subrev_u32_e32 v163, 0x1f03, v169
	v_cndmask_b32_e64 v162, 0, v162, s[36:37]
	v_cndmask_b32_e64 v163, 0, v163, s[50:51]
	v_cndmask_b32_e64 v158, v162, -1, s[34:35]
	v_cndmask_b32_e64 v159, v163, -1, s[48:49]
.Ltk0_tinit:
	s_brev_b32 s20, 1
	s_mov_b32 s21, 0x80002000
	s_branch .Ltk0_bloop
